# DeltaNet: no wait for the next chunk's LDS-DMA prefetch at the pair-dot barrier, gate scalars converted at use, pair-dot LDS reads issued together
# baseline (speedup 1.0000x reference)
; __device__ __forceinline__ float sigm(float x) { return __builtin_amdgcn_rcpf(1.f + __expf(-x)); }
; __device__ __forceinline__ void dn_task(const Params& p, int l, int task, char* smem) {
;     ...
;     if (tid >= 224) {
;       const int t = tid - 224;
;       const float xx = ra + dtb;
;       const float sp = xx > 20.f ? xx : log1pf(__expf(xx));
;       al[t] = __expf(-Aexp * sp);
;       al[32 + t] = sigm(rb);
.LBB0_195:
	s_or_b64 exec, exec, s[70:71]
	s_and_saveexec_b64 s[60:61], s[50:51]
	s_cbranch_execz .LBB0_199
	s_cmp_eq_u32 s81, 0
	s_cbranch_scc1 .Ldn_ab0
	v_lshlrev_b32_e32 v141, 16, v242
	v_lshlrev_b32_e32 v140, 16, v243
.Ldn_ab0:
	v_add_f32_e32 v0, v160, v141
	s_mov_b32 s70, 0x41a00000
	v_cmp_nlt_f32_e32 vcc, s70, v0
	s_and_saveexec_b64 s[70:71], vcc
	s_cbranch_execz .LBB0_198
	v_mul_f32_e32 v0, 0x3fb8aa3b, v0
	v_exp_f32_e32 v0, v0
	s_mov_b32 s82, 0x3f2aaaab
	v_add_f32_e32 v12, 1.0, v0
	v_frexp_mant_f32_e32 v14, v12
	v_cvt_f64_f32_e32 v[10:11], v12
	v_frexp_exp_i32_f64_e32 v10, v[10:11]
	v_cmp_gt_f32_e32 vcc, s82, v14
	v_add_f32_e32 v13, -1.0, v12
	v_sub_f32_e32 v15, v13, v12
	v_subbrev_co_u32_e32 v18, vcc, 0, v10, vcc
	v_sub_u32_e32 v10, 0, v18
	v_sub_f32_e32 v13, v0, v13
	v_add_f32_e32 v15, 1.0, v15
	v_ldexp_f32 v11, v12, v10
	v_add_f32_e32 v13, v13, v15
	v_add_f32_e32 v12, -1.0, v11
	v_add_f32_e32 v14, 1.0, v11
	v_ldexp_f32 v10, v13, v10
	v_add_f32_e32 v13, 1.0, v12
	v_add_f32_e32 v15, -1.0, v14
	v_sub_f32_e32 v13, v11, v13
	v_sub_f32_e32 v11, v11, v15
	v_add_f32_e32 v13, v10, v13
	v_add_f32_e32 v10, v10, v11
	v_add_f32_e32 v19, v14, v10
	v_rcp_f32_e32 v21, v19
	v_sub_f32_e32 v11, v19, v14
	v_sub_f32_e32 v20, v10, v11
	v_add_f32_e32 v11, v12, v13
	v_mul_f32_e32 v23, v11, v21
	v_sub_f32_e32 v10, v11, v12
	v_mul_f32_e32 v12, v19, v23
	v_fma_f32 v14, v23, v19, -v12
	v_fmac_f32_e32 v14, v23, v20
	v_sub_f32_e32 v22, v13, v10
	v_add_f32_e32 v10, v12, v14
	v_sub_f32_e32 v13, v11, v10
	v_pk_add_f32 v[16:17], v[10:11], v[12:13] neg_lo:[0,1] neg_hi:[0,1]
	v_mov_b32_e32 v15, v10
	v_pk_add_f32 v[10:11], v[16:17], v[14:15] neg_lo:[0,1] neg_hi:[0,1]
	s_mov_b32 s82, 0x3f317218
	v_add_f32_e32 v11, v22, v11
	v_add_f32_e32 v10, v10, v11
	v_add_f32_e32 v11, v13, v10
	v_mul_f32_e32 v22, v21, v11
	v_mul_f32_e32 v12, v19, v22
	v_fma_f32 v14, v22, v19, -v12
	v_fmac_f32_e32 v14, v22, v20
	v_sub_f32_e32 v13, v13, v11
	v_add_f32_e32 v19, v10, v13
	v_add_f32_e32 v10, v12, v14
	v_sub_f32_e32 v13, v11, v10
	v_pk_add_f32 v[16:17], v[10:11], v[12:13] neg_lo:[0,1] neg_hi:[0,1]
	v_mov_b32_e32 v15, v10
	v_pk_add_f32 v[10:11], v[16:17], v[14:15] neg_lo:[0,1] neg_hi:[0,1]
	s_nop 0
	v_add_f32_e32 v11, v19, v11
	v_add_f32_e32 v10, v10, v11
	v_add_f32_e32 v11, v23, v22
	v_add_f32_e32 v10, v13, v10
	v_sub_f32_e32 v12, v11, v23
	v_mul_f32_e32 v10, v21, v10
	v_sub_f32_e32 v12, v22, v12
	v_add_f32_e32 v12, v12, v10
	v_add_f32_e32 v14, v11, v12
	v_mul_f32_e32 v15, v14, v14
	v_fmamk_f32 v10, v15, 0x3e9b6dac, v177
	v_fmaak_f32 v135, v15, v10, 0x3f2aaada
	v_cvt_f32_i32_e32 v10, v18
	v_sub_f32_e32 v11, v14, v11
	v_sub_f32_e32 v11, v12, v11
	v_ldexp_f32 v16, v11, 1
	v_mul_f32_e32 v11, v14, v15
	v_ldexp_f32 v13, v14, 1
	v_pk_mul_f32 v[14:15], v[10:11], v[134:135]
	s_nop 0
	v_fma_f32 v12, v10, s82, -v14
	v_fmac_f32_e32 v12, 0xb102e308, v10
	v_pk_add_f32 v[10:11], v[14:15], v[12:13]
	s_mov_b32 s82, 0x7f800000
	v_sub_f32_e32 v13, v11, v13
	v_sub_f32_e32 v13, v15, v13
	v_add_f32_e32 v17, v16, v13
	v_mov_b32_e32 v16, v14
	v_pk_add_f32 v[14:15], v[10:11], v[14:15] neg_lo:[0,1] neg_hi:[0,1]
	v_pk_add_f32 v[18:19], v[10:11], v[16:17]
	v_mov_b32_e32 v13, v10
	v_mov_b32_e32 v15, v19
	v_pk_add_f32 v[20:21], v[12:13], v[14:15] neg_lo:[0,1] neg_hi:[0,1]
	v_pk_add_f32 v[12:13], v[12:13], v[14:15]
	v_mov_b32_e32 v16, v17
	v_pk_add_f32 v[14:15], v[12:13], v[10:11] op_sel:[1,0] op_sel_hi:[0,1] neg_lo:[0,1] neg_hi:[0,1]
	v_pk_add_f32 v[22:23], v[18:19], v[14:15] op_sel_hi:[1,0] neg_lo:[0,1] neg_hi:[0,1]
	v_mov_b32_e32 v18, v19
	v_mov_b32_e32 v19, v13
	v_pk_mov_b32 v[14:15], v[10:11], v[14:15] op_sel:[1,0]
	v_mov_b32_e32 v17, v10
	v_pk_add_f32 v[14:15], v[18:19], v[14:15] neg_lo:[0,1] neg_hi:[0,1]
	v_mov_b32_e32 v22, v20
	v_pk_add_f32 v[10:11], v[16:17], v[14:15] neg_lo:[0,1] neg_hi:[0,1]
	v_mov_b32_e32 v21, v13
	v_pk_add_f32 v[14:15], v[22:23], v[10:11]
	v_cmp_neq_f32_e32 vcc, s82, v0
	v_pk_add_f32 v[16:17], v[14:15], v[14:15] op_sel:[0,1] op_sel_hi:[1,0]
	s_mov_b32 s82, 0x33800000
	v_pk_add_f32 v[12:13], v[12:13], v[16:17] op_sel:[1,0] op_sel_hi:[0,1]
	v_mov_b32_e32 v15, v12
	v_pk_add_f32 v[18:19], v[14:15], v[20:21] neg_lo:[0,1] neg_hi:[0,1]
	v_mov_b32_e32 v11, v16
	v_sub_f32_e32 v13, v14, v18
	v_pk_add_f32 v[10:11], v[10:11], v[18:19] neg_lo:[0,1] neg_hi:[0,1]
	v_sub_f32_e32 v13, v20, v13
	v_add_f32_e32 v10, v10, v13
	v_add_f32_e32 v10, v10, v11
	v_add_f32_e32 v10, v12, v10
	v_cndmask_b32_e32 v10, v181, v10, vcc
	v_cmp_ngt_f32_e32 vcc, -1.0, v0
	s_nop 1
	v_cndmask_b32_e32 v10, v184, v10, vcc
	v_cmp_neq_f32_e32 vcc, -1.0, v0
	s_nop 1
	v_cndmask_b32_e32 v10, v192, v10, vcc
	v_cmp_lt_f32_e64 vcc, |v0|, s82
	s_nop 1
	v_cndmask_b32_e32 v0, v10, v0, vcc

.LBB0_205:
	v_sub_u32_e32 v0, s81, v138
	v_add_u32_e32 v0, 0xff, v0
	v_add_u32_e32 v10, s70, v139
	v_cndmask_b32_e64 v0, v0, v10, s[40:41]
	v_add_u32_e32 v0, s71, v0
	v_mad_i64_i32 v[10:11], s[70:71], v0, s74, v[144:145]
	global_load_ushort v242, v[10:11], off offset:2048
	s_nop 0
	global_load_ushort v243, v[10:11], off offset:2064

; __device__ __forceinline__ void dn_task(const Params& p, int l, int task, char* smem) {
;     ...
;     {
;       const int did = tid >> 2, pp = did >> 2, wh = did & 3, part = tid & 3;
;       const float* xr = (wh == 0) ? (ks + (2 * pp + 1) * 68) : (wh == 1) ? (qs + (2 * pp) * 68) : (qs + (2 * pp + 1) * 68);
;       const float* yr = (wh == 3) ? (ks + (2 * pp + 1) * 68) : (ks + (2 * pp) * 68);
;       float sdot = 0.f;
; #pragma unroll
;       for (int i = 0; i < 16; ++i) sdot += xr[part * 16 + i] * yr[part * 16 + i];
;       sdot = quad_sum(sdot);
;       if (part == 0) dots[did] = sdot;
;     }
;     __syncthreads();
.LBB0_211:
	s_or_b64 exec, exec, s[60:61]
	v_lshl_add_u32 v0, v164, 2, v0
	ds_read_b128 v[10:13], v211 offset:8704
	ds_read_b128 v[14:17], v211 offset:8720
	ds_read_b128 v[18:21], v211 offset:8736
	ds_read_b128 v[22:25], v211 offset:8752
	ds_read2_b32 v[26:27], v0 offset1:1
	ds_read2_b32 v[42:43], v0 offset0:2 offset1:3
	ds_read2_b32 v[44:45], v0 offset0:4 offset1:5
	ds_read2_b32 v[46:47], v0 offset0:6 offset1:7
	ds_read2_b32 v[48:49], v0 offset0:8 offset1:9
	ds_read2_b32 v[50:51], v0 offset0:10 offset1:11
	ds_read2_b32 v[52:53], v0 offset0:12 offset1:13
	ds_read2_b32 v[54:55], v0 offset0:14 offset1:15
	s_waitcnt lgkmcnt(0)
	v_fma_f32 v26, v26, v10, 0
	v_fmac_f32_e32 v26, v27, v11
	v_fmac_f32_e32 v26, v42, v12
	v_fmac_f32_e32 v26, v43, v13
	v_fmac_f32_e32 v26, v44, v14
	v_fmac_f32_e32 v26, v45, v15
	v_fmac_f32_e32 v26, v46, v16
	v_fmac_f32_e32 v26, v47, v17
	v_fmac_f32_e32 v26, v48, v18
	v_fmac_f32_e32 v26, v49, v19
	v_fmac_f32_e32 v26, v50, v20
	v_fmac_f32_e32 v26, v51, v21
	v_fmac_f32_e32 v26, v52, v22
	v_fmac_f32_e32 v26, v53, v23
	v_fmac_f32_e32 v26, v54, v24
	v_fmac_f32_e32 v26, v55, v25
	s_nop 1
	v_add_f32_dpp v0, v26, v26 quad_perm:[1,0,3,2] row_mask:0xf bank_mask:0xf bound_ctrl:1
	s_nop 1
	v_mov_b32_dpp v10, v0 quad_perm:[2,3,0,1] row_mask:0xf bank_mask:0xf bound_ctrl:1
	s_and_saveexec_b64 s[60:61], s[54:55]
	v_add_f32_e32 v0, v0, v10
	ds_write_b32 v197, v0 offset:25856
	s_or_b64 exec, exec, s[60:61]
	s_waitcnt lgkmcnt(0)
	s_barrier
	ds_read_b128 v[34:37], v166
	ds_read_b128 v[30:33], v166 offset:16
	ds_read_b128 v[10:13], v166 offset:8704
	ds_read_b128 v[14:17], v166 offset:8720
	ds_read_b128 v[18:21], v166 offset:8976
	ds_read_b128 v[22:25], v166 offset:8992
	ds_read_b128 v[42:45], v166 offset:272
	ds_read_b128 v[46:49], v166 offset:288
	v_add_u32_e64 v0, s24, 0
	ds_read2_b64 v[26:29], v0 offset0:128 offset1:144
	ds_read2st64_b32 v[156:157], v167 offset0:68 offset1:69
	ds_read_b128 v[38:41], v1 offset:25856
	s_mov_b32 s70, 0
	s_movk_i32 s81, 0x6510
	s_movk_i32 s83, 0x6408
	v_mov_b32_e32 v135, v213
	v_mov_b32_e32 v221, v212
	s_branch .LBB0_215
